# PEER query GEMM k-loop: A/B fragment ds_reads run 4 MFMAs ahead through a 6-slot register ring (counted lgkmcnt) instead of read-wait-MFMA on one register quad
# speedup vs baseline: 1.0052x; 1.0052x over previous
.LBB0_1851:
	s_setprio 2
	ds_read_b128 v[194:197], v164 offset:36864
	ds_read_b128 v[224:227], v189
	ds_read_b128 v[228:231], v189 offset:4608
	ds_read_b128 v[232:235], v189 offset:9216
	ds_read_b128 v[236:239], v189 offset:13824
	s_cmp_gt_u32 s3, 12
	ds_read_b128 v[240:243], v164 offset:36896
	ds_read_b128 v[190:193], v189 offset:32
	s_waitcnt lgkmcnt(5)
	v_mfma_f32_32x32x16_bf16 v[0:15], v[224:227], v[194:197], v[0:15]
	ds_read_b128 v[198:201], v189 offset:4640
	s_waitcnt lgkmcnt(5)
	v_mfma_f32_32x32x16_bf16 v[16:31], v[228:231], v[194:197], v[16:31]
	ds_read_b128 v[224:227], v189 offset:9248
	s_waitcnt lgkmcnt(5)
	v_mfma_f32_32x32x16_bf16 v[34:49], v[232:235], v[194:197], v[34:49]
	ds_read_b128 v[228:231], v189 offset:13856
	s_waitcnt lgkmcnt(5)
	v_mfma_f32_32x32x16_bf16 v[50:65], v[236:239], v[194:197], v[50:65]
	ds_read_b128 v[194:197], v164 offset:36928
	ds_read_b128 v[232:235], v189 offset:64
	s_waitcnt lgkmcnt(5)
	v_mfma_f32_32x32x16_bf16 v[0:15], v[190:193], v[240:243], v[0:15]
	ds_read_b128 v[236:239], v189 offset:4672
	s_waitcnt lgkmcnt(5)
	v_mfma_f32_32x32x16_bf16 v[16:31], v[198:201], v[240:243], v[16:31]
	ds_read_b128 v[190:193], v189 offset:9280
	s_waitcnt lgkmcnt(5)
	v_mfma_f32_32x32x16_bf16 v[34:49], v[224:227], v[240:243], v[34:49]
	ds_read_b128 v[198:201], v189 offset:13888
	s_waitcnt lgkmcnt(5)
	v_mfma_f32_32x32x16_bf16 v[50:65], v[228:231], v[240:243], v[50:65]
	ds_read_b128 v[240:243], v164 offset:36960
	ds_read_b128 v[224:227], v189 offset:96
	s_waitcnt lgkmcnt(5)
	v_mfma_f32_32x32x16_bf16 v[0:15], v[232:235], v[194:197], v[0:15]
	ds_read_b128 v[228:231], v189 offset:4704
	s_waitcnt lgkmcnt(5)
	v_mfma_f32_32x32x16_bf16 v[16:31], v[236:239], v[194:197], v[16:31]
	ds_read_b128 v[232:235], v189 offset:9312
	s_waitcnt lgkmcnt(5)
	v_mfma_f32_32x32x16_bf16 v[34:49], v[190:193], v[194:197], v[34:49]
	ds_read_b128 v[236:239], v189 offset:13920
	s_waitcnt lgkmcnt(5)
	v_mfma_f32_32x32x16_bf16 v[50:65], v[198:201], v[194:197], v[50:65]
	s_waitcnt lgkmcnt(3)
	v_mfma_f32_32x32x16_bf16 v[0:15], v[224:227], v[240:243], v[0:15]
	s_waitcnt lgkmcnt(2)
	v_mfma_f32_32x32x16_bf16 v[16:31], v[228:231], v[240:243], v[16:31]
	s_setprio 0
	s_waitcnt vmcnt(7)
	ds_write_b128 v166, v[130:133] offset:18432
	s_waitcnt vmcnt(1)
	ds_write_b128 v166, v[138:141] offset:55296
	s_waitcnt vmcnt(5)
	ds_write_b128 v166, v[134:137] offset:23040
	s_waitcnt vmcnt(4)
	ds_write_b128 v166, v[146:149] offset:59904
	s_waitcnt vmcnt(3)
	ds_write_b128 v166, v[142:145] offset:27648
	s_waitcnt vmcnt(2)
	ds_write_b128 v166, v[150:153] offset:64512
	s_waitcnt vmcnt(1)
	ds_write_b128 v166, v[154:157] offset:32256
	s_waitcnt vmcnt(0)
	ds_write_b128 v165, v[158:161] offset:13824
	s_waitcnt lgkmcnt(0)
	s_barrier
	v_mfma_f32_32x32x16_bf16 v[34:49], v[232:235], v[240:243], v[34:49]
	v_mfma_f32_32x32x16_bf16 v[50:65], v[236:239], v[240:243], v[50:65]
	s_cbranch_scc1 .LBB0_1853
	v_add_co_u32_e32 v138, vcc, 0x10000, v180
	v_lshl_add_u64 v[130:131], v[168:169], 0, v[32:33]
	s_nop 0
	v_addc_co_u32_e32 v139, vcc, 0, v181, vcc
	v_add_co_u32_e32 v140, vcc, 0x20000, v180
	v_lshl_add_u64 v[134:135], v[170:171], 0, v[32:33]
	s_nop 0
	v_addc_co_u32_e32 v141, vcc, 0, v181, vcc
	v_add_co_u32_e32 v158, vcc, 0x30000, v180
	global_load_dwordx4 v[130:133], v[130:131], off
	s_nop 0
	v_addc_co_u32_e32 v159, vcc, 0, v181, vcc
	global_load_dwordx4 v[134:137], v[134:135], off
	s_nop 0
	global_load_dwordx4 v[142:145], v[184:185], off offset:128
	global_load_dwordx4 v[146:149], v[138:139], off offset:384
	global_load_dwordx4 v[150:153], v[140:141], off offset:384
	global_load_dwordx4 v[154:157], v[182:183], off
	s_nop 0
	global_load_dwordx4 v[138:141], v[180:181], off offset:384
	s_nop 0
	global_load_dwordx4 v[158:161], v[158:159], off offset:384
.LBB0_1853:
	s_setprio 2
	ds_read_b128 v[194:197], v164 offset:55296
	ds_read_b128 v[224:227], v189 offset:18432
	ds_read_b128 v[228:231], v189 offset:23040
	ds_read_b128 v[232:235], v189 offset:27648
	ds_read_b128 v[236:239], v189 offset:32256
	s_andn2_b64 vcc, exec, s[8:9]
	ds_read_b128 v[240:243], v164 offset:55328
	ds_read_b128 v[190:193], v189 offset:18464
	s_waitcnt lgkmcnt(5)
	v_mfma_f32_32x32x16_bf16 v[0:15], v[224:227], v[194:197], v[0:15]
	ds_read_b128 v[198:201], v189 offset:23072
	s_waitcnt lgkmcnt(5)
	v_mfma_f32_32x32x16_bf16 v[16:31], v[228:231], v[194:197], v[16:31]
	ds_read_b128 v[224:227], v189 offset:27680
	s_waitcnt lgkmcnt(5)
	v_mfma_f32_32x32x16_bf16 v[34:49], v[232:235], v[194:197], v[34:49]
	ds_read_b128 v[228:231], v189 offset:32288
	s_waitcnt lgkmcnt(5)
	v_mfma_f32_32x32x16_bf16 v[50:65], v[236:239], v[194:197], v[50:65]
	ds_read_b128 v[194:197], v164 offset:55360
	ds_read_b128 v[232:235], v189 offset:18496
	s_waitcnt lgkmcnt(5)
	v_mfma_f32_32x32x16_bf16 v[0:15], v[190:193], v[240:243], v[0:15]
	ds_read_b128 v[236:239], v189 offset:23104
	s_waitcnt lgkmcnt(5)
	v_mfma_f32_32x32x16_bf16 v[16:31], v[198:201], v[240:243], v[16:31]
	ds_read_b128 v[190:193], v189 offset:27712
	s_waitcnt lgkmcnt(5)
	v_mfma_f32_32x32x16_bf16 v[34:49], v[224:227], v[240:243], v[34:49]
	ds_read_b128 v[198:201], v189 offset:32320
	s_waitcnt lgkmcnt(5)
	v_mfma_f32_32x32x16_bf16 v[50:65], v[228:231], v[240:243], v[50:65]
	ds_read_b128 v[240:243], v164 offset:55392
	ds_read_b128 v[224:227], v189 offset:18528
	s_waitcnt lgkmcnt(5)
	v_mfma_f32_32x32x16_bf16 v[0:15], v[232:235], v[194:197], v[0:15]
	ds_read_b128 v[228:231], v189 offset:23136
	s_waitcnt lgkmcnt(5)
	v_mfma_f32_32x32x16_bf16 v[16:31], v[236:239], v[194:197], v[16:31]
	ds_read_b128 v[232:235], v189 offset:27744
	s_waitcnt lgkmcnt(5)
	v_mfma_f32_32x32x16_bf16 v[34:49], v[190:193], v[194:197], v[34:49]
	ds_read_b128 v[236:239], v189 offset:32352
	s_waitcnt lgkmcnt(5)
	v_mfma_f32_32x32x16_bf16 v[50:65], v[198:201], v[194:197], v[50:65]
	s_waitcnt lgkmcnt(3)
	v_mfma_f32_32x32x16_bf16 v[0:15], v[224:227], v[240:243], v[0:15]
	s_waitcnt lgkmcnt(2)
	v_mfma_f32_32x32x16_bf16 v[16:31], v[228:231], v[240:243], v[16:31]
	s_waitcnt lgkmcnt(1)
	v_mfma_f32_32x32x16_bf16 v[34:49], v[232:235], v[240:243], v[34:49]
	s_waitcnt lgkmcnt(0)
	v_mfma_f32_32x32x16_bf16 v[50:65], v[236:239], v[240:243], v[50:65]
	s_setprio 0
	s_cbranch_vccnz .LBB0_1848
	ds_write_b128 v166, v[66:69]
	ds_write_b128 v166, v[78:81] offset:36864
	ds_write_b128 v166, v[70:73] offset:4608
	ds_write_b128 v166, v[74:77] offset:41472
	ds_write_b128 v166, v[86:89] offset:9216
	ds_write_b128 v166, v[82:85] offset:46080
	ds_write_b128 v166, v[94:97] offset:13824
	ds_write_b128 v166, v[90:93] offset:50688
	s_branch .LBB0_1848
